# w_in epilogue: per-row-block gamma/rotary math regenerated as scalar v_mul/v_fma (no packed ops / register shuffles)
# speedup vs baseline: 1.0167x; 1.0078x over previous
;   DI void operator()(const f32x4 (&acc)[2][2][4][2], const Unit& u, int wr, int wc, int fr, int fq) const {
;     ...
;           float ss = 0.f;
; #pragma unroll
;           for (int bj = 0; bj < 2; ++bj)
; #pragma unroll
;             for (int n = 0; n < 2; ++n)
; #pragma unroll
;               for (int e = 0; e < 4; ++e) ss += acc[ai][bj][m][n][e] * acc[ai][bj][m][n][e];
;           ss += __shfl_xor(ss, 16);
;           ss += __shfl_xor(ss, 32);
;           const float rinv = rsqrtf(ss * (1.f / 64.f) + EPSV);
;           float o1[8], o2[8];
; #pragma unroll
;           for (int n = 0; n < 2; ++n) {
;             f32x4 cs0 = (f32x4){1.f, 0.f, 1.f, 0.f}, cs1 = cs0;
;             if (ropeT) { cs0 = csr[m & 1][n][0]; cs1 = csr[m & 1][n][1]; }
; #pragma unroll
;             for (int e = 0; e < 4; ++e) {
;               float x1 = acc[ai][0][m][n][e] * (rinv * qs) * g4[0][n][e];
;               float x2 = acc[ai][1][m][n][e] * (rinv * qs) * g4[1][n][e];
;               float c = (e < 2) ? cs0[2 * e] : cs1[2 * (e - 2)], s = (e < 2) ? cs0[2 * e + 1] : cs1[2 * (e - 2) + 1];
;               o1[n * 4 + e] = x1 * c - x2 * s;
;               o2[n * 4 + e] = x2 * c + x1 * s;
;             }
;           }
;           u16* dst = base + (size_t)pos * 64 + 8 * fq;
;           *(uint4*)(dst) = make_uint4(pack_bf16(o1[0], o1[1]), pack_bf16(o1[2], o1[3]), pack_bf16(o1[4], o1[5]), pack_bf16(o1[6], o1[7]));
;           *(uint4*)(dst + 32) = make_uint4(pack_bf16(o2[0], o2[1]), pack_bf16(o2[2], o2[3]), pack_bf16(o2[4], o2[5]), pack_bf16(o2[6], o2[7]));
.LBB0_536:
	s_xor_b64 s[52:53], s[8:9], -1
	s_or_b64 s[8:9], s[10:11], s[22:23]
	s_or_b64 vcc, s[24:25], s[8:9]
	s_ashr_i32 s8, s49, 7
	s_andn2_b32 s8, s8, 31
	s_add_i32 s8, s8, s48
	s_mul_hi_i32 s9, s8, 0x88000
	s_mul_i32 s8, s8, 0x88000
	s_add_u32 s10, s88, s8
	v_cndmask_b32_e64 v180, 0, 1, s[52:53]
	v_cndmask_b32_e32 v217, 1.0, v248, vcc
	s_addc_u32 s11, s89, s9
	s_mov_b64 s[22:23], -1
	v_cmp_ne_u32_e64 s[8:9], 1, v180
	s_andn2_b64 vcc, exec, s[52:53]
	v_lshlrev_b32_e32 v206, 1, v184
	s_cbranch_vccnz .LBB0_538
	v_mul_f32_e32 v180, v175, v175
	v_fmac_f32_e32 v180, v174, v174
	v_fmac_f32_e32 v180, v176, v176
	v_fmac_f32_e32 v180, v177, v177
	v_fmac_f32_e32 v180, v170, v170
	v_fmac_f32_e32 v180, v171, v171
	v_fmac_f32_e32 v180, v172, v172
	v_fmac_f32_e32 v180, v173, v173
	v_pk_mul_f32 v[220:221], v[166:167], v[166:167]
	v_pk_mul_f32 v[218:219], v[168:169], v[168:169]
	v_add_f32_e32 v180, v220, v180
	v_add_f32_e32 v180, v221, v180
	v_add_f32_e32 v180, v218, v180
	v_add_f32_e32 v180, v219, v180
	v_pk_mul_f32 v[220:221], v[162:163], v[162:163]
	v_add_f32_e32 v180, v220, v180
	v_pk_mul_f32 v[218:219], v[164:165], v[164:165]
	v_add_f32_e32 v180, v221, v180
	v_add_f32_e32 v180, v218, v180
	v_add_f32_e32 v180, v219, v180
	v_mov_b32_e32 v181, v180
	s_nop 1
	v_permlane16_swap_b32_e32 v180, v181
	s_mov_b32 s22, 0x800000
	s_waitcnt vmcnt(0)
	s_waitcnt lgkmcnt(0)
	v_add_f32_e32 v180, v180, v181
	v_mov_b32_e32 v181, v180
	s_nop 1
	v_permlane32_swap_b32_e32 v180, v181
	s_waitcnt lgkmcnt(0)
	v_add_f32_e32 v180, v180, v181
	v_fmamk_f32 v180, v180, 0x3c800000, v210
	v_mul_f32_e32 v181, 0x4b800000, v180
	v_cmp_gt_f32_e32 vcc, s22, v180
	s_nop 1
	v_cndmask_b32_e32 v180, v180, v181, vcc
	v_rsq_f32_e32 v180, v180
	s_nop 0
	v_mul_f32_e32 v181, 0x45800000, v180
	v_cndmask_b32_e32 v180, v180, v181, vcc
	v_mul_f32_e32 v208, v217, v180
	v_mul_f32_e32 v218, v174, v208
	v_mul_f32_e32 v230, v166, v208
	v_mul_f32_e32 v219, v175, v208
	v_mul_f32_e32 v231, v167, v208
	v_mul_f32_e32 v220, v176, v208
	v_mul_f32_e32 v228, v168, v208
	v_mul_f32_e32 v221, v177, v208
	v_mul_f32_e32 v229, v169, v208
	v_mul_f32_e32 v222, v170, v208
	v_mul_f32_e32 v238, v162, v208
	v_mul_f32_e32 v223, v171, v208
	v_mul_f32_e32 v239, v163, v208
	v_mul_f32_e32 v224, v172, v208
	v_mul_f32_e32 v236, v164, v208
	v_mul_f32_e32 v225, v173, v208
	v_mul_f32_e32 v237, v165, v208
	v_mul_f32_e32 v218, v218, v74
	v_mul_f32_e32 v230, v230, v78
	v_mul_f32_e32 v219, v219, v75
	v_mul_f32_e32 v231, v231, v79
	v_mul_f32_e32 v220, v220, v76
	v_mul_f32_e32 v228, v228, v80
	v_mul_f32_e32 v221, v221, v77
	v_mul_f32_e32 v229, v229, v81
	v_mul_f32_e32 v222, v222, v66
	v_mul_f32_e32 v238, v238, v70
	v_mul_f32_e32 v223, v223, v67
	v_mul_f32_e32 v239, v239, v71
	v_mul_f32_e32 v224, v224, v68
	v_mul_f32_e32 v236, v236, v72
	v_mul_f32_e32 v225, v225, v69
	v_mul_f32_e32 v237, v237, v73
	s_cmp_eq_u64 s[6:7], 0
	s_cbranch_scc1 .Lqkv_norope_0
	v_mul_f32_e32 v232, v230, v127
	v_mul_f32_e32 v233, v218, v127
	v_fma_f32 v218, v218, v126, -v232
	v_fma_f32 v230, v230, v126, v233
	v_mul_f32_e32 v232, v231, v129
	v_mul_f32_e32 v233, v219, v129
	v_fma_f32 v219, v219, v128, -v232
	v_fma_f32 v231, v231, v128, v233
	v_mul_f32_e32 v232, v228, v123
	v_mul_f32_e32 v233, v220, v123
	v_fma_f32 v220, v220, v122, -v232
	v_fma_f32 v228, v228, v122, v233
	v_mul_f32_e32 v232, v229, v125
	v_mul_f32_e32 v233, v221, v125
	v_fma_f32 v221, v221, v124, -v232
	v_fma_f32 v229, v229, v124, v233
	v_mul_f32_e32 v232, v238, v119
	v_mul_f32_e32 v233, v222, v119
	v_fma_f32 v222, v222, v118, -v232
	v_fma_f32 v238, v238, v118, v233
	v_mul_f32_e32 v232, v239, v121
	v_mul_f32_e32 v233, v223, v121
	v_fma_f32 v223, v223, v120, -v232
	v_fma_f32 v239, v239, v120, v233
	v_mul_f32_e32 v232, v236, v115
	v_mul_f32_e32 v233, v224, v115
	v_fma_f32 v224, v224, v114, -v232
	v_fma_f32 v236, v236, v114, v233
	v_mul_f32_e32 v232, v237, v117
	v_mul_f32_e32 v233, v225, v117
	v_fma_f32 v225, v225, v116, -v232
	v_fma_f32 v237, v237, v116, v233
.Lqkv_norope_0:
	v_lshlrev_b32_e32 v226, 7, v209
	v_mov_b32_e32 v227, v1
	v_lshl_add_u64 v[226:227], s[10:11], 0, v[226:227]
	v_mov_b32_e32 v207, v1
	v_lshl_add_u64 v[226:227], v[226:227], 0, v[206:207]
	v_cvt_pk_bf16_f32 v218, v218, v219
	v_cvt_pk_bf16_f32 v219, v220, v221
	v_cvt_pk_bf16_f32 v220, v222, v223
	v_cvt_pk_bf16_f32 v221, v224, v225
	global_store_dwordx4 v[226:227], v[218:221], off
	s_mov_b64 s[22:23], 0
	s_nop 0
	v_cvt_pk_bf16_f32 v218, v230, v231
	v_cvt_pk_bf16_f32 v219, v228, v229
	v_cvt_pk_bf16_f32 v220, v238, v239
	v_cvt_pk_bf16_f32 v221, v236, v237
	global_store_dwordx4 v[226:227], v[218:221], off offset:64

;   DI void operator()(const f32x4 (&acc)[2][2][4][2], const Unit& u, int wr, int wc, int fr, int fq) const {
;     ...
;           float ss = 0.f;
; #pragma unroll
;           for (int bj = 0; bj < 2; ++bj)
; #pragma unroll
;             for (int n = 0; n < 2; ++n)
; #pragma unroll
;               for (int e = 0; e < 4; ++e) ss += acc[ai][bj][m][n][e] * acc[ai][bj][m][n][e];
;           ss += __shfl_xor(ss, 16);
;           ss += __shfl_xor(ss, 32);
;           const float rinv = rsqrtf(ss * (1.f / 64.f) + EPSV);
;           float o1[8], o2[8];
; #pragma unroll
;           for (int n = 0; n < 2; ++n) {
;             f32x4 cs0 = (f32x4){1.f, 0.f, 1.f, 0.f}, cs1 = cs0;
;             if (ropeT) { cs0 = csr[m & 1][n][0]; cs1 = csr[m & 1][n][1]; }
; #pragma unroll
;             for (int e = 0; e < 4; ++e) {
;               float x1 = acc[ai][0][m][n][e] * (rinv * qs) * g4[0][n][e];
;               float x2 = acc[ai][1][m][n][e] * (rinv * qs) * g4[1][n][e];
;               float c = (e < 2) ? cs0[2 * e] : cs1[2 * (e - 2)], s = (e < 2) ? cs0[2 * e + 1] : cs1[2 * (e - 2) + 1];
;               o1[n * 4 + e] = x1 * c - x2 * s;
;               o2[n * 4 + e] = x2 * c + x1 * s;
;             }
;           }
;           u16* dst = base + (size_t)pos * 64 + 8 * fq;
;           *(uint4*)(dst) = make_uint4(pack_bf16(o1[0], o1[1]), pack_bf16(o1[2], o1[3]), pack_bf16(o1[4], o1[5]), pack_bf16(o1[6], o1[7]));
;           *(uint4*)(dst + 32) = make_uint4(pack_bf16(o2[0], o2[1]), pack_bf16(o2[2], o2[3]), pack_bf16(o2[4], o2[5]), pack_bf16(o2[6], o2[7]));
.LBB0_540:
	s_add_i32 s10, s50, s42
	s_and_b32 s11, s10, 0xfd0
	s_ashr_i32 s10, s10, 7
	s_andn2_b32 s10, s10, 31
	s_add_i32 s10, s10, s48
	v_or_b32_e32 v162, s11, v214
	s_mul_hi_i32 s11, s10, 0x88000
	s_mul_i32 s10, s10, 0x88000
	s_add_u32 s10, s88, s10
	s_addc_u32 s11, s89, s11
	s_and_b64 vcc, exec, s[8:9]
	s_mov_b64 s[22:23], -1
	v_readlane_b32 s52, v253, 59
	v_readlane_b32 s53, v253, 60
	s_cbranch_vccnz .LBB0_542
	v_mul_f32_e32 v163, v159, v159
	v_fmac_f32_e32 v163, v158, v158
	v_fmac_f32_e32 v163, v160, v160
	v_fmac_f32_e32 v163, v161, v161
	v_fmac_f32_e32 v163, v154, v154
	v_fmac_f32_e32 v163, v155, v155
	v_fmac_f32_e32 v163, v156, v156
	v_fmac_f32_e32 v163, v157, v157
	v_pk_mul_f32 v[166:167], v[150:151], v[150:151]
	v_pk_mul_f32 v[164:165], v[152:153], v[152:153]
	v_add_f32_e32 v163, v166, v163
	v_add_f32_e32 v163, v167, v163
	v_add_f32_e32 v163, v164, v163
	v_add_f32_e32 v163, v165, v163
	v_pk_mul_f32 v[166:167], v[146:147], v[146:147]
	v_pk_mul_f32 v[164:165], v[148:149], v[148:149]
	v_add_f32_e32 v163, v166, v163
	v_add_f32_e32 v163, v167, v163
	v_add_f32_e32 v163, v164, v163
	v_add_f32_e32 v163, v165, v163
	s_mov_b32 s22, 0x800000
	v_mov_b32_e32 v164, v163
	s_nop 1
	v_permlane16_swap_b32_e32 v163, v164
	s_waitcnt lgkmcnt(0)
	v_add_f32_e32 v163, v163, v164
	v_mov_b32_e32 v164, v163
	s_nop 1
	v_permlane32_swap_b32_e32 v163, v164
	s_waitcnt lgkmcnt(0)
	v_add_f32_e32 v163, v163, v164
	v_fmamk_f32 v163, v163, 0x3c800000, v210
	v_mul_f32_e32 v164, 0x4b800000, v163
	v_cmp_gt_f32_e32 vcc, s22, v163
	s_nop 1
	v_cndmask_b32_e32 v163, v163, v164, vcc
	v_rsq_f32_e32 v163, v163
	s_nop 0
	v_mul_f32_e32 v164, 0x45800000, v163
	v_cndmask_b32_e32 v163, v163, v164, vcc
	v_mul_f32_e32 v164, v217, v163
	v_mul_f32_e32 v166, v158, v164
	v_mul_f32_e32 v218, v150, v164
	v_mul_f32_e32 v167, v159, v164
	v_mul_f32_e32 v219, v151, v164
	v_mul_f32_e32 v168, v160, v164
	v_mul_f32_e32 v176, v152, v164
	v_mul_f32_e32 v169, v161, v164
	v_mul_f32_e32 v177, v153, v164
	v_mul_f32_e32 v170, v154, v164
	v_mul_f32_e32 v226, v146, v164
	v_mul_f32_e32 v171, v155, v164
	v_mul_f32_e32 v227, v147, v164
	v_mul_f32_e32 v172, v156, v164
	v_mul_f32_e32 v222, v148, v164
	v_mul_f32_e32 v173, v157, v164
	v_mul_f32_e32 v223, v149, v164
	v_mul_f32_e32 v166, v166, v74
	v_mul_f32_e32 v218, v218, v78
	v_mul_f32_e32 v167, v167, v75
	v_mul_f32_e32 v219, v219, v79
	v_mul_f32_e32 v168, v168, v76
	v_mul_f32_e32 v176, v176, v80
	v_mul_f32_e32 v169, v169, v77
	v_mul_f32_e32 v177, v177, v81
	v_mul_f32_e32 v170, v170, v66
	v_mul_f32_e32 v226, v226, v70
	v_mul_f32_e32 v171, v171, v67
	v_mul_f32_e32 v227, v227, v71
	v_mul_f32_e32 v172, v172, v68
	v_mul_f32_e32 v222, v222, v72
	v_mul_f32_e32 v173, v173, v69
	v_mul_f32_e32 v223, v223, v73
	s_cmp_eq_u64 s[6:7], 0
	s_cbranch_scc1 .Lqkv_norope_1
	v_mul_f32_e32 v220, v218, v95
	v_mul_f32_e32 v221, v166, v95
	v_fma_f32 v166, v166, v94, -v220
	v_fma_f32 v218, v218, v94, v221
	v_mul_f32_e32 v220, v219, v97
	v_mul_f32_e32 v221, v167, v97
	v_fma_f32 v167, v167, v96, -v220
	v_fma_f32 v219, v219, v96, v221
	v_mul_f32_e32 v220, v176, v99
	v_mul_f32_e32 v221, v168, v99
	v_fma_f32 v168, v168, v98, -v220
	v_fma_f32 v176, v176, v98, v221
	v_mul_f32_e32 v220, v177, v101
	v_mul_f32_e32 v221, v169, v101
	v_fma_f32 v169, v169, v100, -v220
	v_fma_f32 v177, v177, v100, v221
	v_mul_f32_e32 v220, v226, v87
	v_mul_f32_e32 v221, v170, v87
	v_fma_f32 v170, v170, v86, -v220
	v_fma_f32 v226, v226, v86, v221
	v_mul_f32_e32 v220, v227, v89
	v_mul_f32_e32 v221, v171, v89
	v_fma_f32 v171, v171, v88, -v220
	v_fma_f32 v227, v227, v88, v221
	v_mul_f32_e32 v220, v222, v83
	v_mul_f32_e32 v221, v172, v83
	v_fma_f32 v172, v172, v82, -v220
	v_fma_f32 v222, v222, v82, v221
	v_mul_f32_e32 v220, v223, v85
	v_mul_f32_e32 v221, v173, v85
	v_fma_f32 v173, v173, v84, -v220
	v_fma_f32 v223, v223, v84, v221
.Lqkv_norope_1:
	v_mov_b32_e32 v207, v1
	v_lshlrev_b32_e32 v164, 7, v162
	v_mov_b32_e32 v165, v1
	v_lshl_add_u64 v[164:165], s[10:11], 0, v[164:165]
	v_lshl_add_u64 v[174:175], v[164:165], 0, v[206:207]
	v_cvt_pk_bf16_f32 v164, v166, v167
	v_cvt_pk_bf16_f32 v165, v168, v169
	v_cvt_pk_bf16_f32 v166, v170, v171
	v_cvt_pk_bf16_f32 v167, v172, v173
	global_store_dwordx4 v[174:175], v[164:167], off
	s_mov_b64 s[22:23], 0
	s_nop 0
	v_cvt_pk_bf16_f32 v164, v218, v219
	v_cvt_pk_bf16_f32 v165, v176, v177
	v_cvt_pk_bf16_f32 v166, v226, v227
	v_cvt_pk_bf16_f32 v167, v222, v223
	global_store_dwordx4 v[174:175], v[164:167], off offset:64

;   DI void operator()(const f32x4 (&acc)[2][2][4][2], const Unit& u, int wr, int wc, int fr, int fq) const {
;     ...
;           const int tt = u.pm * BM + ai * HALF + wr * 64 + (2 * mp + m2) * 16 + fr;
;           const float* rp = rope + (size_t)(tt & 4095) * 64 + 2 * (8 * fq);
; #pragma unroll
;           for (int n = 0; n < 2; ++n) { csr[m2][n][0] = *(const f32x4*)(rp + 8 * n); csr[m2][n][1] = *(const f32x4*)(rp + 8 * n + 4); }
;         }
;     ...
;           float ss = 0.f;
; #pragma unroll
;           for (int bj = 0; bj < 2; ++bj)
; #pragma unroll
;             for (int n = 0; n < 2; ++n)
; #pragma unroll
;               for (int e = 0; e < 4; ++e) ss += acc[ai][bj][m][n][e] * acc[ai][bj][m][n][e];
;           ss += __shfl_xor(ss, 16);
;           ss += __shfl_xor(ss, 32);
;           const float rinv = rsqrtf(ss * (1.f / 64.f) + EPSV);
;           float o1[8], o2[8];
; #pragma unroll
;           for (int n = 0; n < 2; ++n) {
;             f32x4 cs0 = (f32x4){1.f, 0.f, 1.f, 0.f}, cs1 = cs0;
;             if (ropeT) { cs0 = csr[m & 1][n][0]; cs1 = csr[m & 1][n][1]; }
; #pragma unroll
;             for (int e = 0; e < 4; ++e) {
;               float x1 = acc[ai][0][m][n][e] * (rinv * qs) * g4[0][n][e];
;               float x2 = acc[ai][1][m][n][e] * (rinv * qs) * g4[1][n][e];
;               float c = (e < 2) ? cs0[2 * e] : cs1[2 * (e - 2)], s = (e < 2) ? cs0[2 * e + 1] : cs1[2 * (e - 2) + 1];
;               o1[n * 4 + e] = x1 * c - x2 * s;
;               o2[n * 4 + e] = x2 * c + x1 * s;
;             }
;           }
;           u16* dst = base + (size_t)pos * 64 + 8 * fq;
;           *(uint4*)(dst) = make_uint4(pack_bf16(o1[0], o1[1]), pack_bf16(o1[2], o1[3]), pack_bf16(o1[4], o1[5]), pack_bf16(o1[6], o1[7]));
;           *(uint4*)(dst + 32) = make_uint4(pack_bf16(o2[0], o2[1]), pack_bf16(o2[2], o2[3]), pack_bf16(o2[4], o2[5]), pack_bf16(o2[6], o2[7]));
.LBB0_546:
	s_add_i32 s2, s50, s43
	s_and_b32 s3, s2, 0xfe0
	s_ashr_i32 s2, s2, 7
	s_andn2_b32 s2, s2, 31
	s_add_i32 s2, s2, s48
	v_or_b32_e32 v146, s3, v214
	s_mul_hi_i32 s3, s2, 0x88000
	s_mul_i32 s2, s2, 0x88000
	s_add_u32 s2, s88, s2
	s_addc_u32 s3, s89, s3
	s_and_b64 vcc, exec, s[8:9]
	s_mov_b64 s[22:23], -1
	s_cbranch_vccnz .LBB0_548
	v_mul_f32_e32 v0, v143, v143
	v_fmac_f32_e32 v0, v142, v142
	v_fmac_f32_e32 v0, v144, v144
	v_fmac_f32_e32 v0, v145, v145
	v_fmac_f32_e32 v0, v138, v138
	v_fmac_f32_e32 v0, v139, v139
	v_fmac_f32_e32 v0, v140, v140
	v_fmac_f32_e32 v0, v141, v141
	v_pk_mul_f32 v[150:151], v[134:135], v[134:135]
	v_pk_mul_f32 v[148:149], v[136:137], v[136:137]
	v_add_f32_e32 v0, v150, v0
	v_add_f32_e32 v0, v151, v0
	v_add_f32_e32 v0, v148, v0
	v_add_f32_e32 v0, v149, v0
	v_pk_mul_f32 v[150:151], v[130:131], v[130:131]
	v_pk_mul_f32 v[148:149], v[132:133], v[132:133]
	v_add_f32_e32 v0, v150, v0
	v_add_f32_e32 v0, v151, v0
	v_add_f32_e32 v0, v148, v0
	v_add_f32_e32 v0, v149, v0
	s_mov_b32 s22, 0x800000
	v_mov_b32_e32 v147, v0
	s_nop 1
	v_permlane16_swap_b32_e32 v0, v147
	s_waitcnt vmcnt(0)
	s_waitcnt lgkmcnt(0)
	v_add_f32_e32 v0, v0, v147
	v_mov_b32_e32 v147, v0
	s_nop 1
	v_permlane32_swap_b32_e32 v0, v147
	s_waitcnt lgkmcnt(0)
	v_add_f32_e32 v0, v0, v147
	v_fmamk_f32 v0, v0, 0x3c800000, v210
	v_mul_f32_e32 v147, 0x4b800000, v0
	v_cmp_gt_f32_e32 vcc, s22, v0
	s_nop 1
	v_cndmask_b32_e32 v0, v0, v147, vcc
	v_rsq_f32_e32 v0, v0
	s_nop 0
	v_mul_f32_e32 v147, 0x45800000, v0
	v_cndmask_b32_e32 v0, v0, v147, vcc
	v_mul_f32_e32 v0, v217, v0
	v_mul_f32_e32 v148, v142, v0
	v_mul_f32_e32 v160, v134, v0
	v_mul_f32_e32 v149, v143, v0
	v_mul_f32_e32 v161, v135, v0
	v_mul_f32_e32 v150, v144, v0
	v_mul_f32_e32 v158, v136, v0
	v_mul_f32_e32 v151, v145, v0
	v_mul_f32_e32 v159, v137, v0
	v_mul_f32_e32 v152, v138, v0
	v_mul_f32_e32 v168, v130, v0
	v_mul_f32_e32 v153, v139, v0
	v_mul_f32_e32 v169, v131, v0
	v_mul_f32_e32 v154, v140, v0
	v_mul_f32_e32 v166, v132, v0
	v_mul_f32_e32 v155, v141, v0
	v_mul_f32_e32 v167, v133, v0
	v_mul_f32_e32 v148, v148, v74
	v_mul_f32_e32 v160, v160, v78
	v_mul_f32_e32 v149, v149, v75
	v_mul_f32_e32 v161, v161, v79
	v_mul_f32_e32 v150, v150, v76
	v_mul_f32_e32 v158, v158, v80
	v_mul_f32_e32 v151, v151, v77
	v_mul_f32_e32 v159, v159, v81
	v_mul_f32_e32 v152, v152, v66
	v_mul_f32_e32 v168, v168, v70
	v_mul_f32_e32 v153, v153, v67
	v_mul_f32_e32 v169, v169, v71
	v_mul_f32_e32 v154, v154, v68
	v_mul_f32_e32 v166, v166, v72
	v_mul_f32_e32 v155, v155, v69
	v_mul_f32_e32 v167, v167, v73
	s_cmp_eq_u64 s[6:7], 0
	s_cbranch_scc1 .Lqkv_norope_2
	v_mul_f32_e32 v162, v160, v127
	v_mul_f32_e32 v163, v148, v127
	v_fma_f32 v148, v148, v126, -v162
	v_fma_f32 v160, v160, v126, v163
	v_mul_f32_e32 v162, v161, v129
	v_mul_f32_e32 v163, v149, v129
	v_fma_f32 v149, v149, v128, -v162
	v_fma_f32 v161, v161, v128, v163
	v_mul_f32_e32 v162, v158, v123
	v_mul_f32_e32 v163, v150, v123
	v_fma_f32 v150, v150, v122, -v162
	v_fma_f32 v158, v158, v122, v163
	v_mul_f32_e32 v162, v159, v125
	v_mul_f32_e32 v163, v151, v125
	v_fma_f32 v151, v151, v124, -v162
	v_fma_f32 v159, v159, v124, v163
	v_mul_f32_e32 v162, v168, v119
	v_mul_f32_e32 v163, v152, v119
	v_fma_f32 v152, v152, v118, -v162
	v_fma_f32 v168, v168, v118, v163
	v_mul_f32_e32 v162, v169, v121
	v_mul_f32_e32 v163, v153, v121
	v_fma_f32 v153, v153, v120, -v162
	v_fma_f32 v169, v169, v120, v163
	v_mul_f32_e32 v162, v166, v115
	v_mul_f32_e32 v163, v154, v115
	v_fma_f32 v154, v154, v114, -v162
	v_fma_f32 v166, v166, v114, v163
	v_mul_f32_e32 v162, v167, v117
	v_mul_f32_e32 v163, v155, v117
	v_fma_f32 v155, v155, v116, -v162
	v_fma_f32 v167, v167, v116, v163
.Lqkv_norope_2:
	v_lshlrev_b32_e32 v0, 7, v146
	v_lshl_add_u64 v[156:157], s[2:3], 0, v[0:1]
	v_mov_b32_e32 v207, v1
	v_lshl_add_u64 v[156:157], v[156:157], 0, v[206:207]
	v_cvt_pk_bf16_f32 v148, v148, v149
	v_cvt_pk_bf16_f32 v149, v150, v151
	v_cvt_pk_bf16_f32 v150, v152, v153
	v_cvt_pk_bf16_f32 v151, v154, v155
	global_store_dwordx4 v[156:157], v[148:151], off
	s_mov_b64 s[22:23], 0
	s_nop 0
	v_cvt_pk_bf16_f32 v148, v160, v161
	v_cvt_pk_bf16_f32 v149, v158, v159
	v_cvt_pk_bf16_f32 v150, v168, v169
	v_cvt_pk_bf16_f32 v151, v166, v167
	global_store_dwordx4 v[156:157], v[148:151], off offset:64

;   DI void operator()(const f32x4 (&acc)[2][2][4][2], const Unit& u, int wr, int wc, int fr, int fq) const {
;     ...
;           float ss = 0.f;
; #pragma unroll
;           for (int bj = 0; bj < 2; ++bj)
; #pragma unroll
;             for (int n = 0; n < 2; ++n)
; #pragma unroll
;               for (int e = 0; e < 4; ++e) ss += acc[ai][bj][m][n][e] * acc[ai][bj][m][n][e];
;           ss += __shfl_xor(ss, 16);
;           ss += __shfl_xor(ss, 32);
;           const float rinv = rsqrtf(ss * (1.f / 64.f) + EPSV);
;           float o1[8], o2[8];
; #pragma unroll
;           for (int n = 0; n < 2; ++n) {
;             f32x4 cs0 = (f32x4){1.f, 0.f, 1.f, 0.f}, cs1 = cs0;
;             if (ropeT) { cs0 = csr[m & 1][n][0]; cs1 = csr[m & 1][n][1]; }
; #pragma unroll
;             for (int e = 0; e < 4; ++e) {
;               float x1 = acc[ai][0][m][n][e] * (rinv * qs) * g4[0][n][e];
;               float x2 = acc[ai][1][m][n][e] * (rinv * qs) * g4[1][n][e];
;               float c = (e < 2) ? cs0[2 * e] : cs1[2 * (e - 2)], s = (e < 2) ? cs0[2 * e + 1] : cs1[2 * (e - 2) + 1];
;               o1[n * 4 + e] = x1 * c - x2 * s;
;               o2[n * 4 + e] = x2 * c + x1 * s;
;             }
;           }
;           u16* dst = base + (size_t)pos * 64 + 8 * fq;
;           *(uint4*)(dst) = make_uint4(pack_bf16(o1[0], o1[1]), pack_bf16(o1[2], o1[3]), pack_bf16(o1[4], o1[5]), pack_bf16(o1[6], o1[7]));
;           *(uint4*)(dst + 32) = make_uint4(pack_bf16(o2[0], o2[1]), pack_bf16(o2[2], o2[3]), pack_bf16(o2[4], o2[5]), pack_bf16(o2[6], o2[7]));
.LBB0_550:
	s_add_i32 s50, s50, s44
	s_and_b32 s2, s50, 0xff0
	v_or_b32_e32 v130, s2, v214
	s_ashr_i32 s2, s50, 7
	s_andn2_b32 s2, s2, 31
	s_add_i32 s2, s2, s48
	s_mul_hi_i32 s3, s2, 0x88000
	s_mul_i32 s2, s2, 0x88000
	s_add_u32 s2, s88, s2
	s_addc_u32 s3, s89, s3
	s_and_b64 vcc, exec, s[8:9]
	s_mov_b64 s[22:23], -1
	s_cbranch_vccnz .LBB0_552
	v_mul_f32_e32 v0, v111, v111
	v_fmac_f32_e32 v0, v110, v110
	v_fmac_f32_e32 v0, v112, v112
	v_fmac_f32_e32 v0, v113, v113
	v_fmac_f32_e32 v0, v106, v106
	v_fmac_f32_e32 v0, v107, v107
	v_fmac_f32_e32 v0, v108, v108
	v_fmac_f32_e32 v0, v109, v109
	v_pk_mul_f32 v[134:135], v[102:103], v[102:103]
	v_pk_mul_f32 v[132:133], v[104:105], v[104:105]
	v_add_f32_e32 v0, v134, v0
	v_add_f32_e32 v0, v135, v0
	v_add_f32_e32 v0, v132, v0
	v_add_f32_e32 v0, v133, v0
	v_pk_mul_f32 v[134:135], v[90:91], v[90:91]
	v_pk_mul_f32 v[132:133], v[92:93], v[92:93]
	v_add_f32_e32 v0, v134, v0
	v_add_f32_e32 v0, v135, v0
	v_add_f32_e32 v0, v132, v0
	v_add_f32_e32 v0, v133, v0
	s_mov_b32 s22, 0x800000
	v_mov_b32_e32 v131, v0
	s_nop 1
	v_permlane16_swap_b32_e32 v0, v131
	s_waitcnt lgkmcnt(0)
	v_add_f32_e32 v0, v0, v131
	v_mov_b32_e32 v131, v0
	s_nop 1
	v_permlane32_swap_b32_e32 v0, v131
	s_waitcnt lgkmcnt(0)
	v_add_f32_e32 v0, v0, v131
	v_fmamk_f32 v0, v0, 0x3c800000, v210
	v_mul_f32_e32 v131, 0x4b800000, v0
	v_cmp_gt_f32_e32 vcc, s22, v0
	s_nop 1
	v_cndmask_b32_e32 v0, v0, v131, vcc
	v_rsq_f32_e32 v0, v0
	s_nop 0
	v_mul_f32_e32 v131, 0x45800000, v0
	v_cndmask_b32_e32 v0, v0, v131, vcc
	v_mul_f32_e32 v0, v217, v0
	v_mul_f32_e32 v132, v110, v0
	v_mul_f32_e32 v144, v102, v0
	v_mul_f32_e32 v133, v111, v0
	v_mul_f32_e32 v145, v103, v0
	v_mul_f32_e32 v134, v112, v0
	v_mul_f32_e32 v142, v104, v0
	v_mul_f32_e32 v135, v113, v0
	v_mul_f32_e32 v143, v105, v0
	v_mul_f32_e32 v136, v106, v0
	v_mul_f32_e32 v152, v90, v0
	v_mul_f32_e32 v137, v107, v0
	v_mul_f32_e32 v153, v91, v0
	v_mul_f32_e32 v138, v108, v0
	v_mul_f32_e32 v150, v92, v0
	v_mul_f32_e32 v139, v109, v0
	v_mul_f32_e32 v151, v93, v0
	v_mul_f32_e32 v132, v132, v74
	v_mul_f32_e32 v144, v144, v78
	v_mul_f32_e32 v133, v133, v75
	v_mul_f32_e32 v145, v145, v79
	v_mul_f32_e32 v134, v134, v76
	v_mul_f32_e32 v142, v142, v80
	v_mul_f32_e32 v135, v135, v77
	v_mul_f32_e32 v143, v143, v81
	v_mul_f32_e32 v136, v136, v66
	v_mul_f32_e32 v152, v152, v70
	v_mul_f32_e32 v137, v137, v67
	v_mul_f32_e32 v153, v153, v71
	v_mul_f32_e32 v138, v138, v68
	v_mul_f32_e32 v150, v150, v72
	v_mul_f32_e32 v139, v139, v69
	v_mul_f32_e32 v151, v151, v73
	s_cmp_eq_u64 s[6:7], 0
	s_cbranch_scc1 .Lqkv_norope_3
	v_mul_f32_e32 v146, v144, v95
	v_mul_f32_e32 v147, v132, v95
	v_fma_f32 v132, v132, v94, -v146
	v_fma_f32 v144, v144, v94, v147
	v_mul_f32_e32 v146, v145, v97
	v_mul_f32_e32 v147, v133, v97
	v_fma_f32 v133, v133, v96, -v146
	v_fma_f32 v145, v145, v96, v147
	v_mul_f32_e32 v146, v142, v99
	v_mul_f32_e32 v147, v134, v99
	v_fma_f32 v134, v134, v98, -v146
	v_fma_f32 v142, v142, v98, v147
	v_mul_f32_e32 v146, v143, v101
	v_mul_f32_e32 v147, v135, v101
	v_fma_f32 v135, v135, v100, -v146
	v_fma_f32 v143, v143, v100, v147
	v_mul_f32_e32 v146, v152, v87
	v_mul_f32_e32 v147, v136, v87
	v_fma_f32 v136, v136, v86, -v146
	v_fma_f32 v152, v152, v86, v147
	v_mul_f32_e32 v146, v153, v89
	v_mul_f32_e32 v147, v137, v89
	v_fma_f32 v137, v137, v88, -v146
	v_fma_f32 v153, v153, v88, v147
	v_mul_f32_e32 v146, v150, v83
	v_mul_f32_e32 v147, v138, v83
	v_fma_f32 v138, v138, v82, -v146
	v_fma_f32 v150, v150, v82, v147
	v_mul_f32_e32 v146, v151, v85
	v_mul_f32_e32 v147, v139, v85
	v_fma_f32 v139, v139, v84, -v146
	v_fma_f32 v151, v151, v84, v147
.Lqkv_norope_3:
	v_lshlrev_b32_e32 v0, 7, v130
	v_lshl_add_u64 v[140:141], s[2:3], 0, v[0:1]
	v_mov_b32_e32 v207, v1
	v_lshl_add_u64 v[140:141], v[140:141], 0, v[206:207]
	v_cvt_pk_bf16_f32 v132, v132, v133
	v_cvt_pk_bf16_f32 v133, v134, v135
	v_cvt_pk_bf16_f32 v134, v136, v137
	v_cvt_pk_bf16_f32 v135, v138, v139
	global_store_dwordx4 v[140:141], v[132:135], off
	s_mov_b64 s[22:23], 0
	s_nop 0
	v_cvt_pk_bf16_f32 v132, v144, v145
	v_cvt_pk_bf16_f32 v133, v142, v143
	v_cvt_pk_bf16_f32 v134, v152, v153
	v_cvt_pk_bf16_f32 v135, v150, v151
	global_store_dwordx4 v[140:141], v[132:135], off offset:64

;   DI void operator()(const f32x4 (&acc)[2][2][4][2], const Unit& u, int wr, int wc, int fr, int fq) const {
;     ...
;           const int tt = u.pm * BM + ai * HALF + wr * 64 + (2 * mp + m2) * 16 + fr;
;           const float* rp = rope + (size_t)(tt & 4095) * 64 + 2 * (8 * fq);
; #pragma unroll
;           for (int n = 0; n < 2; ++n) { csr[m2][n][0] = *(const f32x4*)(rp + 8 * n); csr[m2][n][1] = *(const f32x4*)(rp + 8 * n + 4); }
;         }
;     ...
;           float ss = 0.f;
; #pragma unroll
;           for (int bj = 0; bj < 2; ++bj)
; #pragma unroll
;             for (int n = 0; n < 2; ++n)
; #pragma unroll
;               for (int e = 0; e < 4; ++e) ss += acc[ai][bj][m][n][e] * acc[ai][bj][m][n][e];
;           ss += __shfl_xor(ss, 16);
;           ss += __shfl_xor(ss, 32);
;           const float rinv = rsqrtf(ss * (1.f / 64.f) + EPSV);
;           float o1[8], o2[8];
; #pragma unroll
;           for (int n = 0; n < 2; ++n) {
;             f32x4 cs0 = (f32x4){1.f, 0.f, 1.f, 0.f}, cs1 = cs0;
;             if (ropeT) { cs0 = csr[m & 1][n][0]; cs1 = csr[m & 1][n][1]; }
; #pragma unroll
;             for (int e = 0; e < 4; ++e) {
;               float x1 = acc[ai][0][m][n][e] * (rinv * qs) * g4[0][n][e];
;               float x2 = acc[ai][1][m][n][e] * (rinv * qs) * g4[1][n][e];
;               float c = (e < 2) ? cs0[2 * e] : cs1[2 * (e - 2)], s = (e < 2) ? cs0[2 * e + 1] : cs1[2 * (e - 2) + 1];
;               o1[n * 4 + e] = x1 * c - x2 * s;
;               o2[n * 4 + e] = x2 * c + x1 * s;
;             }
;           }
;           u16* dst = base + (size_t)pos * 64 + 8 * fq;
;           *(uint4*)(dst) = make_uint4(pack_bf16(o1[0], o1[1]), pack_bf16(o1[2], o1[3]), pack_bf16(o1[4], o1[5]), pack_bf16(o1[6], o1[7]));
;           *(uint4*)(dst + 32) = make_uint4(pack_bf16(o2[0], o2[1]), pack_bf16(o2[2], o2[3]), pack_bf16(o2[4], o2[5]), pack_bf16(o2[6], o2[7]));
.LBB0_556:
	s_ashr_i32 s2, s2, 7
	s_andn2_b32 s2, s2, 31
	s_add_i32 s2, s2, s48
	s_mul_hi_i32 s3, s2, 0x88000
	s_mul_i32 s2, s2, 0x88000
	s_add_u32 s2, s88, s2
	s_addc_u32 s3, s89, s3
	s_and_b64 vcc, exec, s[8:9]
	s_mov_b64 s[22:23], -1
	s_cbranch_vccnz .LBB0_558
	v_mul_f32_e32 v91, v63, v63
	v_fmac_f32_e32 v91, v62, v62
	v_fmac_f32_e32 v91, v64, v64
	v_fmac_f32_e32 v91, v65, v65
	v_fmac_f32_e32 v91, v58, v58
	v_fmac_f32_e32 v91, v59, v59
	v_fmac_f32_e32 v91, v60, v60
	v_fmac_f32_e32 v91, v61, v61
	v_pk_mul_f32 v[102:103], v[54:55], v[54:55]
	v_pk_mul_f32 v[92:93], v[56:57], v[56:57]
	v_add_f32_e32 v91, v102, v91
	v_add_f32_e32 v91, v103, v91
	v_add_f32_e32 v91, v92, v91
	v_add_f32_e32 v91, v93, v91
	v_pk_mul_f32 v[102:103], v[50:51], v[50:51]
	v_pk_mul_f32 v[92:93], v[52:53], v[52:53]
	v_add_f32_e32 v91, v102, v91
	v_add_f32_e32 v91, v103, v91
	v_add_f32_e32 v91, v92, v91
	v_add_f32_e32 v91, v93, v91
	s_mov_b32 s22, 0x800000
	v_mov_b32_e32 v92, v91
	s_nop 1
	v_permlane16_swap_b32_e32 v91, v92
	s_waitcnt vmcnt(0)
	s_waitcnt lgkmcnt(0)
	v_add_f32_e32 v91, v91, v92
	v_mov_b32_e32 v92, v91
	s_nop 1
	v_permlane32_swap_b32_e32 v91, v92
	s_waitcnt lgkmcnt(0)
	v_add_f32_e32 v91, v91, v92
	v_fmamk_f32 v91, v91, 0x3c800000, v210
	v_mul_f32_e32 v92, 0x4b800000, v91
	v_cmp_gt_f32_e32 vcc, s22, v91
	s_nop 1
	v_cndmask_b32_e32 v91, v91, v92, vcc
	v_rsq_f32_e32 v91, v91
	s_nop 0
	v_mul_f32_e32 v92, 0x45800000, v91
	v_cndmask_b32_e32 v91, v91, v92, vcc
	v_mul_f32_e32 v92, v217, v91
	v_mul_f32_e32 v102, v62, v92
	v_mul_f32_e32 v130, v54, v92
	v_mul_f32_e32 v103, v63, v92
	v_mul_f32_e32 v131, v55, v92
	v_mul_f32_e32 v104, v64, v92
	v_mul_f32_e32 v112, v56, v92
	v_mul_f32_e32 v105, v65, v92
	v_mul_f32_e32 v113, v57, v92
	v_mul_f32_e32 v106, v58, v92
	v_mul_f32_e32 v138, v50, v92
	v_mul_f32_e32 v107, v59, v92
	v_mul_f32_e32 v139, v51, v92
	v_mul_f32_e32 v134, v52, v92
	v_mul_f32_e32 v93, v61, v92
	v_mul_f32_e32 v135, v53, v92
	v_mul_f32_e32 v92, v60, v92
	v_mul_f32_e32 v102, v102, v74
	v_mul_f32_e32 v130, v130, v78
	v_mul_f32_e32 v103, v103, v75
	v_mul_f32_e32 v131, v131, v79
	v_mul_f32_e32 v104, v104, v76
	v_mul_f32_e32 v112, v112, v80
	v_mul_f32_e32 v105, v105, v77
	v_mul_f32_e32 v113, v113, v81
	v_mul_f32_e32 v106, v106, v66
	v_mul_f32_e32 v138, v138, v70
	v_mul_f32_e32 v107, v107, v67
	v_mul_f32_e32 v139, v139, v71
	v_mul_f32_e32 v134, v134, v72
	v_mul_f32_e32 v93, v93, v69
	v_mul_f32_e32 v135, v135, v73
	v_mul_f32_e32 v92, v92, v68
	s_cmp_eq_u64 s[6:7], 0
	s_cbranch_scc1 .Lqkv_norope_4
	v_mul_f32_e32 v110, v130, v127
	v_mul_f32_e32 v111, v102, v127
	v_fma_f32 v102, v102, v126, -v110
	v_fma_f32 v130, v130, v126, v111
	v_mul_f32_e32 v110, v131, v129
	v_mul_f32_e32 v111, v103, v129
	v_fma_f32 v103, v103, v128, -v110
	v_fma_f32 v131, v131, v128, v111
	v_mul_f32_e32 v110, v112, v123
	v_mul_f32_e32 v111, v104, v123
	v_fma_f32 v104, v104, v122, -v110
	v_fma_f32 v112, v112, v122, v111
	v_mul_f32_e32 v110, v113, v125
	v_mul_f32_e32 v111, v105, v125
	v_fma_f32 v105, v105, v124, -v110
	v_fma_f32 v113, v113, v124, v111
	v_mul_f32_e32 v110, v138, v119
	v_mul_f32_e32 v111, v106, v119
	v_fma_f32 v106, v106, v118, -v110
	v_fma_f32 v138, v138, v118, v111
	v_mul_f32_e32 v110, v139, v121
	v_mul_f32_e32 v111, v107, v121
	v_fma_f32 v107, v107, v120, -v110
	v_fma_f32 v139, v139, v120, v111
	v_mul_f32_e32 v110, v134, v115
	v_mul_f32_e32 v111, v92, v115
	v_fma_f32 v92, v92, v114, -v110
	v_fma_f32 v134, v134, v114, v111
	v_mul_f32_e32 v110, v135, v117
	v_mul_f32_e32 v111, v93, v117
	v_fma_f32 v93, v93, v116, -v110
	v_fma_f32 v135, v135, v116, v111
.Lqkv_norope_4:
	v_lshlrev_b32_e32 v108, 7, v90
	v_mov_b32_e32 v109, v1
	v_lshl_add_u64 v[108:109], s[2:3], 0, v[108:109]
	v_mov_b32_e32 v207, v1
	v_lshl_add_u64 v[108:109], v[108:109], 0, v[206:207]
	v_cvt_pk_bf16_f32 v102, v102, v103
	v_cvt_pk_bf16_f32 v103, v104, v105
	v_cvt_pk_bf16_f32 v104, v106, v107
	v_cvt_pk_bf16_f32 v105, v92, v93
	global_store_dwordx4 v[108:109], v[102:105], off
	s_mov_b64 s[22:23], 0
	s_nop 0
	v_cvt_pk_bf16_f32 v102, v130, v131
	v_cvt_pk_bf16_f32 v103, v112, v113
	v_cvt_pk_bf16_f32 v104, v138, v139
	v_cvt_pk_bf16_f32 v105, v134, v135
	global_store_dwordx4 v[108:109], v[102:105], off offset:64

;   DI void operator()(const f32x4 (&acc)[2][2][4][2], const Unit& u, int wr, int wc, int fr, int fq) const {
;     ...
;           float ss = 0.f;
; #pragma unroll
;           for (int bj = 0; bj < 2; ++bj)
; #pragma unroll
;             for (int n = 0; n < 2; ++n)
; #pragma unroll
;               for (int e = 0; e < 4; ++e) ss += acc[ai][bj][m][n][e] * acc[ai][bj][m][n][e];
;           ss += __shfl_xor(ss, 16);
;           ss += __shfl_xor(ss, 32);
;           const float rinv = rsqrtf(ss * (1.f / 64.f) + EPSV);
;           float o1[8], o2[8];
; #pragma unroll
;           for (int n = 0; n < 2; ++n) {
;             f32x4 cs0 = (f32x4){1.f, 0.f, 1.f, 0.f}, cs1 = cs0;
;             if (ropeT) { cs0 = csr[m & 1][n][0]; cs1 = csr[m & 1][n][1]; }
; #pragma unroll
;             for (int e = 0; e < 4; ++e) {
;               float x1 = acc[ai][0][m][n][e] * (rinv * qs) * g4[0][n][e];
;               float x2 = acc[ai][1][m][n][e] * (rinv * qs) * g4[1][n][e];
;               float c = (e < 2) ? cs0[2 * e] : cs1[2 * (e - 2)], s = (e < 2) ? cs0[2 * e + 1] : cs1[2 * (e - 2) + 1];
;               o1[n * 4 + e] = x1 * c - x2 * s;
;               o2[n * 4 + e] = x2 * c + x1 * s;
;             }
;           }
;           u16* dst = base + (size_t)pos * 64 + 8 * fq;
;           *(uint4*)(dst) = make_uint4(pack_bf16(o1[0], o1[1]), pack_bf16(o1[2], o1[3]), pack_bf16(o1[4], o1[5]), pack_bf16(o1[6], o1[7]));
;           *(uint4*)(dst + 32) = make_uint4(pack_bf16(o2[0], o2[1]), pack_bf16(o2[2], o2[3]), pack_bf16(o2[4], o2[5]), pack_bf16(o2[6], o2[7]));
.LBB0_560:
	s_add_i32 s2, s49, 0x90
	s_and_b32 s3, s2, 0xfd0
	s_ashr_i32 s2, s2, 7
	s_andn2_b32 s2, s2, 31
	s_add_i32 s2, s2, s48
	v_or_b32_e32 v50, s3, v214
	s_mul_hi_i32 s3, s2, 0x88000
	s_mul_i32 s2, s2, 0x88000
	s_add_u32 s2, s88, s2
	s_addc_u32 s3, s89, s3
	s_and_b64 vcc, exec, s[8:9]
	s_mov_b64 s[22:23], -1
	s_cbranch_vccnz .LBB0_572
	v_mul_f32_e32 v51, v47, v47
	v_fmac_f32_e32 v51, v46, v46
	v_fmac_f32_e32 v51, v48, v48
	v_fmac_f32_e32 v51, v49, v49
	v_fmac_f32_e32 v51, v42, v42
	v_fmac_f32_e32 v51, v43, v43
	v_fmac_f32_e32 v51, v44, v44
	v_fmac_f32_e32 v51, v45, v45
	v_pk_mul_f32 v[54:55], v[38:39], v[38:39]
	v_pk_mul_f32 v[52:53], v[40:41], v[40:41]
	v_add_f32_e32 v51, v54, v51
	v_add_f32_e32 v51, v55, v51
	v_add_f32_e32 v51, v52, v51
	v_add_f32_e32 v51, v53, v51
	v_pk_mul_f32 v[54:55], v[34:35], v[34:35]
	v_pk_mul_f32 v[52:53], v[36:37], v[36:37]
	v_add_f32_e32 v51, v54, v51
	v_add_f32_e32 v51, v55, v51
	v_add_f32_e32 v51, v52, v51
	v_add_f32_e32 v51, v53, v51
	s_mov_b32 s22, 0x800000
	v_mov_b32_e32 v52, v51
	s_nop 1
	v_permlane16_swap_b32_e32 v51, v52
	s_waitcnt lgkmcnt(0)
	v_add_f32_e32 v51, v51, v52
	v_mov_b32_e32 v52, v51
	s_nop 1
	v_permlane32_swap_b32_e32 v51, v52
	s_waitcnt lgkmcnt(0)
	v_add_f32_e32 v51, v51, v52
	v_fmamk_f32 v51, v51, 0x3c800000, v210
	v_mul_f32_e32 v52, 0x4b800000, v51
	v_cmp_gt_f32_e32 vcc, s22, v51
	s_nop 1
	v_cndmask_b32_e32 v51, v51, v52, vcc
	v_rsq_f32_e32 v51, v51
	s_nop 0
	v_mul_f32_e32 v52, 0x45800000, v51
	v_cndmask_b32_e32 v51, v51, v52, vcc
	v_mul_f32_e32 v52, v217, v51
	v_mul_f32_e32 v54, v46, v52
	v_mul_f32_e32 v90, v38, v52
	v_mul_f32_e32 v55, v47, v52
	v_mul_f32_e32 v91, v39, v52
	v_mul_f32_e32 v56, v48, v52
	v_mul_f32_e32 v64, v40, v52
	v_mul_f32_e32 v57, v49, v52
	v_mul_f32_e32 v65, v41, v52
	v_mul_f32_e32 v58, v42, v52
	v_mul_f32_e32 v106, v34, v52
	v_mul_f32_e32 v59, v43, v52
	v_mul_f32_e32 v107, v35, v52
	v_mul_f32_e32 v60, v44, v52
	v_mul_f32_e32 v102, v36, v52
	v_mul_f32_e32 v61, v45, v52
	v_mul_f32_e32 v103, v37, v52
	v_mul_f32_e32 v54, v54, v74
	v_mul_f32_e32 v90, v90, v78
	v_mul_f32_e32 v55, v55, v75
	v_mul_f32_e32 v91, v91, v79
	v_mul_f32_e32 v56, v56, v76
	v_mul_f32_e32 v64, v64, v80
	v_mul_f32_e32 v57, v57, v77
	v_mul_f32_e32 v65, v65, v81
	v_mul_f32_e32 v58, v58, v66
	v_mul_f32_e32 v106, v106, v70
	v_mul_f32_e32 v59, v59, v67
	v_mul_f32_e32 v107, v107, v71
	v_mul_f32_e32 v60, v60, v68
	v_mul_f32_e32 v102, v102, v72
	v_mul_f32_e32 v61, v61, v69
	v_mul_f32_e32 v103, v103, v73
	s_cmp_eq_u64 s[6:7], 0
	s_cbranch_scc1 .Lqkv_norope_5
	v_mul_f32_e32 v92, v90, v95
	v_mul_f32_e32 v93, v54, v95
	v_fma_f32 v54, v54, v94, -v92
	v_fma_f32 v90, v90, v94, v93
	v_mul_f32_e32 v92, v91, v97
	v_mul_f32_e32 v93, v55, v97
	v_fma_f32 v55, v55, v96, -v92
	v_fma_f32 v91, v91, v96, v93
	v_mul_f32_e32 v92, v64, v99
	v_mul_f32_e32 v93, v56, v99
	v_fma_f32 v56, v56, v98, -v92
	v_fma_f32 v64, v64, v98, v93
	v_mul_f32_e32 v92, v65, v101
	v_mul_f32_e32 v93, v57, v101
	v_fma_f32 v57, v57, v100, -v92
	v_fma_f32 v65, v65, v100, v93
	v_mul_f32_e32 v92, v106, v87
	v_mul_f32_e32 v93, v58, v87
	v_fma_f32 v58, v58, v86, -v92
	v_fma_f32 v106, v106, v86, v93
	v_mul_f32_e32 v92, v107, v89
	v_mul_f32_e32 v93, v59, v89
	v_fma_f32 v59, v59, v88, -v92
	v_fma_f32 v107, v107, v88, v93
	v_mul_f32_e32 v92, v102, v83
	v_mul_f32_e32 v93, v60, v83
	v_fma_f32 v60, v60, v82, -v92
	v_fma_f32 v102, v102, v82, v93
	v_mul_f32_e32 v92, v103, v85
	v_mul_f32_e32 v93, v61, v85
	v_fma_f32 v61, v61, v84, -v92
	v_fma_f32 v103, v103, v84, v93
.Lqkv_norope_5:
	v_mov_b32_e32 v207, v1
	v_lshlrev_b32_e32 v52, 7, v50
	v_mov_b32_e32 v53, v1
	v_lshl_add_u64 v[52:53], s[2:3], 0, v[52:53]
	v_lshl_add_u64 v[62:63], v[52:53], 0, v[206:207]
	v_cvt_pk_bf16_f32 v52, v54, v55
	v_cvt_pk_bf16_f32 v53, v56, v57
	v_cvt_pk_bf16_f32 v54, v58, v59
	v_cvt_pk_bf16_f32 v55, v60, v61
	global_store_dwordx4 v[62:63], v[52:55], off
	s_nop 1
	v_cvt_pk_bf16_f32 v52, v90, v91
	v_cvt_pk_bf16_f32 v53, v64, v65
	v_cvt_pk_bf16_f32 v54, v106, v107
	v_cvt_pk_bf16_f32 v55, v102, v103
	global_store_dwordx4 v[62:63], v[52:55], off offset:64
	s_cbranch_execz .LBB0_573

;   DI void operator()(const f32x4 (&acc)[2][2][4][2], const Unit& u, int wr, int wc, int fr, int fq) const {
;     ...
;           const int tt = u.pm * BM + ai * HALF + wr * 64 + (2 * mp + m2) * 16 + fr;
;           const float* rp = rope + (size_t)(tt & 4095) * 64 + 2 * (8 * fq);
; #pragma unroll
;           for (int n = 0; n < 2; ++n) { csr[m2][n][0] = *(const f32x4*)(rp + 8 * n); csr[m2][n][1] = *(const f32x4*)(rp + 8 * n + 4); }
;         }
;     ...
;           float ss = 0.f;
; #pragma unroll
;           for (int bj = 0; bj < 2; ++bj)
; #pragma unroll
;             for (int n = 0; n < 2; ++n)
; #pragma unroll
;               for (int e = 0; e < 4; ++e) ss += acc[ai][bj][m][n][e] * acc[ai][bj][m][n][e];
;           ss += __shfl_xor(ss, 16);
;           ss += __shfl_xor(ss, 32);
;           const float rinv = rsqrtf(ss * (1.f / 64.f) + EPSV);
;           float o1[8], o2[8];
; #pragma unroll
;           for (int n = 0; n < 2; ++n) {
;             f32x4 cs0 = (f32x4){1.f, 0.f, 1.f, 0.f}, cs1 = cs0;
;             if (ropeT) { cs0 = csr[m & 1][n][0]; cs1 = csr[m & 1][n][1]; }
; #pragma unroll
;             for (int e = 0; e < 4; ++e) {
;               float x1 = acc[ai][0][m][n][e] * (rinv * qs) * g4[0][n][e];
;               float x2 = acc[ai][1][m][n][e] * (rinv * qs) * g4[1][n][e];
;               float c = (e < 2) ? cs0[2 * e] : cs1[2 * (e - 2)], s = (e < 2) ? cs0[2 * e + 1] : cs1[2 * (e - 2) + 1];
;               o1[n * 4 + e] = x1 * c - x2 * s;
;               o2[n * 4 + e] = x2 * c + x1 * s;
;             }
;           }
;           u16* dst = base + (size_t)pos * 64 + 8 * fq;
;           *(uint4*)(dst) = make_uint4(pack_bf16(o1[0], o1[1]), pack_bf16(o1[2], o1[3]), pack_bf16(o1[4], o1[5]), pack_bf16(o1[6], o1[7]));
;           *(uint4*)(dst + 32) = make_uint4(pack_bf16(o2[0], o2[1]), pack_bf16(o2[2], o2[3]), pack_bf16(o2[4], o2[5]), pack_bf16(o2[6], o2[7]));
.LBB0_564:
	s_add_i32 s2, s49, 0xa0
	s_and_b32 s3, s2, 0xfe0
	s_ashr_i32 s2, s2, 7
	s_andn2_b32 s2, s2, 31
	s_add_i32 s2, s2, s48
	v_or_b32_e32 v34, s3, v214
	s_mul_hi_i32 s3, s2, 0x88000
	s_mul_i32 s2, s2, 0x88000
	s_add_u32 s2, s88, s2
	s_addc_u32 s3, s89, s3
	s_and_b64 vcc, exec, s[8:9]
	s_mov_b64 s[10:11], -1
	s_cbranch_vccnz .LBB0_566
	v_mul_f32_e32 v0, v31, v31
	v_fmac_f32_e32 v0, v30, v30
	v_fmac_f32_e32 v0, v32, v32
	v_fmac_f32_e32 v0, v33, v33
	v_fmac_f32_e32 v0, v26, v26
	v_fmac_f32_e32 v0, v27, v27
	v_fmac_f32_e32 v0, v28, v28
	v_fmac_f32_e32 v0, v29, v29
	v_pk_mul_f32 v[38:39], v[22:23], v[22:23]
	v_pk_mul_f32 v[36:37], v[24:25], v[24:25]
	v_add_f32_e32 v0, v38, v0
	v_add_f32_e32 v0, v39, v0
	v_add_f32_e32 v0, v36, v0
	v_add_f32_e32 v0, v37, v0
	v_pk_mul_f32 v[38:39], v[18:19], v[18:19]
	v_pk_mul_f32 v[36:37], v[20:21], v[20:21]
	v_add_f32_e32 v0, v38, v0
	v_add_f32_e32 v0, v39, v0
	v_add_f32_e32 v0, v36, v0
	v_add_f32_e32 v0, v37, v0
	s_mov_b32 s10, 0x800000
	v_mov_b32_e32 v35, v0
	s_nop 1
	v_permlane16_swap_b32_e32 v0, v35
	s_waitcnt vmcnt(0)
	s_waitcnt lgkmcnt(0)
	v_add_f32_e32 v0, v0, v35
	v_mov_b32_e32 v35, v0
	s_nop 1
	v_permlane32_swap_b32_e32 v0, v35
	s_waitcnt lgkmcnt(0)
	v_add_f32_e32 v0, v0, v35
	v_fmamk_f32 v0, v0, 0x3c800000, v210
	v_mul_f32_e32 v35, 0x4b800000, v0
	v_cmp_gt_f32_e32 vcc, s10, v0
	s_nop 1
	v_cndmask_b32_e32 v0, v0, v35, vcc
	v_rsq_f32_e32 v0, v0
	s_nop 0
	v_mul_f32_e32 v35, 0x45800000, v0
	v_cndmask_b32_e32 v0, v0, v35, vcc
	v_mul_f32_e32 v0, v217, v0
	v_mul_f32_e32 v36, v30, v0
	v_mul_f32_e32 v48, v22, v0
	v_mul_f32_e32 v37, v31, v0
	v_mul_f32_e32 v49, v23, v0
	v_mul_f32_e32 v38, v32, v0
	v_mul_f32_e32 v46, v24, v0
	v_mul_f32_e32 v39, v33, v0
	v_mul_f32_e32 v47, v25, v0
	v_mul_f32_e32 v40, v26, v0
	v_mul_f32_e32 v56, v18, v0
	v_mul_f32_e32 v41, v27, v0
	v_mul_f32_e32 v57, v19, v0
	v_mul_f32_e32 v42, v28, v0
	v_mul_f32_e32 v54, v20, v0
	v_mul_f32_e32 v43, v29, v0
	v_mul_f32_e32 v55, v21, v0
	v_mul_f32_e32 v36, v36, v74
	v_mul_f32_e32 v48, v48, v78
	v_mul_f32_e32 v37, v37, v75
	v_mul_f32_e32 v49, v49, v79
	v_mul_f32_e32 v38, v38, v76
	v_mul_f32_e32 v46, v46, v80
	v_mul_f32_e32 v39, v39, v77
	v_mul_f32_e32 v47, v47, v81
	v_mul_f32_e32 v40, v40, v66
	v_mul_f32_e32 v56, v56, v70
	v_mul_f32_e32 v41, v41, v67
	v_mul_f32_e32 v57, v57, v71
	v_mul_f32_e32 v42, v42, v68
	v_mul_f32_e32 v54, v54, v72
	v_mul_f32_e32 v43, v43, v69
	v_mul_f32_e32 v55, v55, v73
	s_cmp_eq_u64 s[6:7], 0
	s_cbranch_scc1 .Lqkv_norope_6
	v_mul_f32_e32 v50, v48, v127
	v_mul_f32_e32 v51, v36, v127
	v_fma_f32 v36, v36, v126, -v50
	v_fma_f32 v48, v48, v126, v51
	v_mul_f32_e32 v50, v49, v129
	v_mul_f32_e32 v51, v37, v129
	v_fma_f32 v37, v37, v128, -v50
	v_fma_f32 v49, v49, v128, v51
	v_mul_f32_e32 v50, v46, v123
	v_mul_f32_e32 v51, v38, v123
	v_fma_f32 v38, v38, v122, -v50
	v_fma_f32 v46, v46, v122, v51
	v_mul_f32_e32 v50, v47, v125
	v_mul_f32_e32 v51, v39, v125
	v_fma_f32 v39, v39, v124, -v50
	v_fma_f32 v47, v47, v124, v51
	v_mul_f32_e32 v50, v56, v119
	v_mul_f32_e32 v51, v40, v119
	v_fma_f32 v40, v40, v118, -v50
	v_fma_f32 v56, v56, v118, v51
	v_mul_f32_e32 v50, v57, v121
	v_mul_f32_e32 v51, v41, v121
	v_fma_f32 v41, v41, v120, -v50
	v_fma_f32 v57, v57, v120, v51
	v_mul_f32_e32 v50, v54, v115
	v_mul_f32_e32 v51, v42, v115
	v_fma_f32 v42, v42, v114, -v50
	v_fma_f32 v54, v54, v114, v51
	v_mul_f32_e32 v50, v55, v117
	v_mul_f32_e32 v51, v43, v117
	v_fma_f32 v43, v43, v116, -v50
	v_fma_f32 v55, v55, v116, v51
.Lqkv_norope_6:
	v_lshlrev_b32_e32 v0, 7, v34
	v_lshl_add_u64 v[44:45], s[2:3], 0, v[0:1]
	v_mov_b32_e32 v207, v1
	v_lshl_add_u64 v[44:45], v[44:45], 0, v[206:207]
	v_cvt_pk_bf16_f32 v36, v36, v37
	v_cvt_pk_bf16_f32 v37, v38, v39
	v_cvt_pk_bf16_f32 v38, v40, v41
	v_cvt_pk_bf16_f32 v39, v42, v43
	global_store_dwordx4 v[44:45], v[36:39], off
	s_mov_b64 s[10:11], 0
	s_nop 0
	v_cvt_pk_bf16_f32 v36, v48, v49
	v_cvt_pk_bf16_f32 v37, v46, v47
	v_cvt_pk_bf16_f32 v38, v56, v57
	v_cvt_pk_bf16_f32 v39, v54, v55
	global_store_dwordx4 v[44:45], v[36:39], off offset:64

;   DI void operator()(const f32x4 (&acc)[2][2][4][2], const Unit& u, int wr, int wc, int fr, int fq) const {
;     ...
;           float ss = 0.f;
; #pragma unroll
;           for (int bj = 0; bj < 2; ++bj)
; #pragma unroll
;             for (int n = 0; n < 2; ++n)
; #pragma unroll
;               for (int e = 0; e < 4; ++e) ss += acc[ai][bj][m][n][e] * acc[ai][bj][m][n][e];
;           ss += __shfl_xor(ss, 16);
;           ss += __shfl_xor(ss, 32);
;           const float rinv = rsqrtf(ss * (1.f / 64.f) + EPSV);
;           float o1[8], o2[8];
; #pragma unroll
;           for (int n = 0; n < 2; ++n) {
;             f32x4 cs0 = (f32x4){1.f, 0.f, 1.f, 0.f}, cs1 = cs0;
;             if (ropeT) { cs0 = csr[m & 1][n][0]; cs1 = csr[m & 1][n][1]; }
; #pragma unroll
;             for (int e = 0; e < 4; ++e) {
;               float x1 = acc[ai][0][m][n][e] * (rinv * qs) * g4[0][n][e];
;               float x2 = acc[ai][1][m][n][e] * (rinv * qs) * g4[1][n][e];
;               float c = (e < 2) ? cs0[2 * e] : cs1[2 * (e - 2)], s = (e < 2) ? cs0[2 * e + 1] : cs1[2 * (e - 2) + 1];
;               o1[n * 4 + e] = x1 * c - x2 * s;
;               o2[n * 4 + e] = x2 * c + x1 * s;
;             }
;           }
;           u16* dst = base + (size_t)pos * 64 + 8 * fq;
;           *(uint4*)(dst) = make_uint4(pack_bf16(o1[0], o1[1]), pack_bf16(o1[2], o1[3]), pack_bf16(o1[4], o1[5]), pack_bf16(o1[6], o1[7]));
;           *(uint4*)(dst + 32) = make_uint4(pack_bf16(o2[0], o2[1]), pack_bf16(o2[2], o2[3]), pack_bf16(o2[4], o2[5]), pack_bf16(o2[6], o2[7]));
.LBB0_568:
	s_addk_i32 s49, 0xb0
	s_and_b32 s2, s49, 0xff0
	v_or_b32_e32 v18, s2, v214
	s_ashr_i32 s2, s49, 7
	s_andn2_b32 s2, s2, 31
	s_add_i32 s2, s2, s48
	s_mul_hi_i32 s3, s2, 0x88000
	s_mul_i32 s2, s2, 0x88000
	s_add_u32 s2, s88, s2
	s_addc_u32 s3, s89, s3
	s_and_b64 vcc, exec, s[8:9]
	s_mov_b64 s[8:9], -1
	s_cbranch_vccnz .LBB0_570
	v_mul_f32_e32 v0, v15, v15
	v_fmac_f32_e32 v0, v14, v14
	v_fmac_f32_e32 v0, v16, v16
	v_fmac_f32_e32 v0, v17, v17
	v_fmac_f32_e32 v0, v10, v10
	v_fmac_f32_e32 v0, v11, v11
	v_fmac_f32_e32 v0, v12, v12
	v_fmac_f32_e32 v0, v13, v13
	v_pk_mul_f32 v[22:23], v[6:7], v[6:7]
	v_pk_mul_f32 v[20:21], v[8:9], v[8:9]
	v_add_f32_e32 v0, v22, v0
	v_add_f32_e32 v0, v23, v0
	v_add_f32_e32 v0, v20, v0
	v_add_f32_e32 v0, v21, v0
	v_pk_mul_f32 v[22:23], v[2:3], v[2:3]
	v_pk_mul_f32 v[20:21], v[4:5], v[4:5]
	v_add_f32_e32 v0, v22, v0
	v_add_f32_e32 v0, v23, v0
	v_add_f32_e32 v0, v20, v0
	v_add_f32_e32 v0, v21, v0
	s_mov_b32 s8, 0x800000
	v_mov_b32_e32 v19, v0
	s_nop 1
	v_permlane16_swap_b32_e32 v0, v19
	s_waitcnt lgkmcnt(0)
	v_add_f32_e32 v0, v0, v19
	v_mov_b32_e32 v19, v0
	s_nop 1
	v_permlane32_swap_b32_e32 v0, v19
	s_waitcnt lgkmcnt(0)
	v_add_f32_e32 v0, v0, v19
	v_fmamk_f32 v0, v0, 0x3c800000, v210
	v_mul_f32_e32 v19, 0x4b800000, v0
	v_cmp_gt_f32_e32 vcc, s8, v0
	s_nop 1
	v_cndmask_b32_e32 v0, v0, v19, vcc
	v_rsq_f32_e32 v0, v0
	s_nop 0
	v_mul_f32_e32 v19, 0x45800000, v0
	v_cndmask_b32_e32 v0, v0, v19, vcc
	v_mul_f32_e32 v0, v217, v0
	v_mul_f32_e32 v20, v14, v0
	v_mul_f32_e32 v32, v6, v0
	v_mul_f32_e32 v21, v15, v0
	v_mul_f32_e32 v33, v7, v0
	v_mul_f32_e32 v22, v16, v0
	v_mul_f32_e32 v30, v8, v0
	v_mul_f32_e32 v23, v17, v0
	v_mul_f32_e32 v31, v9, v0
	v_mul_f32_e32 v24, v10, v0
	v_mul_f32_e32 v40, v2, v0
	v_mul_f32_e32 v25, v11, v0
	v_mul_f32_e32 v41, v3, v0
	v_mul_f32_e32 v26, v12, v0
	v_mul_f32_e32 v38, v4, v0
	v_mul_f32_e32 v27, v13, v0
	v_mul_f32_e32 v39, v5, v0
	v_mul_f32_e32 v20, v20, v74
	v_mul_f32_e32 v32, v32, v78
	v_mul_f32_e32 v21, v21, v75
	v_mul_f32_e32 v33, v33, v79
	v_mul_f32_e32 v22, v22, v76
	v_mul_f32_e32 v30, v30, v80
	v_mul_f32_e32 v23, v23, v77
	v_mul_f32_e32 v31, v31, v81
	v_mul_f32_e32 v24, v24, v66
	v_mul_f32_e32 v40, v40, v70
	v_mul_f32_e32 v25, v25, v67
	v_mul_f32_e32 v41, v41, v71
	v_mul_f32_e32 v26, v26, v68
	v_mul_f32_e32 v38, v38, v72
	v_mul_f32_e32 v27, v27, v69
	v_mul_f32_e32 v39, v39, v73
	s_cmp_eq_u64 s[6:7], 0
	s_cbranch_scc1 .Lqkv_norope_7
	v_mul_f32_e32 v34, v32, v95
	v_mul_f32_e32 v35, v20, v95
	v_fma_f32 v20, v20, v94, -v34
	v_fma_f32 v32, v32, v94, v35
	v_mul_f32_e32 v34, v33, v97
	v_mul_f32_e32 v35, v21, v97
	v_fma_f32 v21, v21, v96, -v34
	v_fma_f32 v33, v33, v96, v35
	v_mul_f32_e32 v34, v30, v99
	v_mul_f32_e32 v35, v22, v99
	v_fma_f32 v22, v22, v98, -v34
	v_fma_f32 v30, v30, v98, v35
	v_mul_f32_e32 v34, v31, v101
	v_mul_f32_e32 v35, v23, v101
	v_fma_f32 v23, v23, v100, -v34
	v_fma_f32 v31, v31, v100, v35
	v_mul_f32_e32 v34, v40, v87
	v_mul_f32_e32 v35, v24, v87
	v_fma_f32 v24, v24, v86, -v34
	v_fma_f32 v40, v40, v86, v35
	v_mul_f32_e32 v34, v41, v89
	v_mul_f32_e32 v35, v25, v89
	v_fma_f32 v25, v25, v88, -v34
	v_fma_f32 v41, v41, v88, v35
	v_mul_f32_e32 v34, v38, v83
	v_mul_f32_e32 v35, v26, v83
	v_fma_f32 v26, v26, v82, -v34
	v_fma_f32 v38, v38, v82, v35
	v_mul_f32_e32 v34, v39, v85
	v_mul_f32_e32 v35, v27, v85
	v_fma_f32 v27, v27, v84, -v34
	v_fma_f32 v39, v39, v84, v35
.Lqkv_norope_7:
	v_lshlrev_b32_e32 v0, 7, v18
	v_lshl_add_u64 v[28:29], s[2:3], 0, v[0:1]
	v_mov_b32_e32 v207, v1
	v_lshl_add_u64 v[28:29], v[28:29], 0, v[206:207]
	v_cvt_pk_bf16_f32 v20, v20, v21
	v_cvt_pk_bf16_f32 v21, v22, v23
	v_cvt_pk_bf16_f32 v22, v24, v25
	v_cvt_pk_bf16_f32 v23, v26, v27
	global_store_dwordx4 v[28:29], v[20:23], off
	s_mov_b64 s[8:9], 0
	s_nop 0
	v_cvt_pk_bf16_f32 v20, v32, v33
	v_cvt_pk_bf16_f32 v21, v30, v31
	v_cvt_pk_bf16_f32 v22, v40, v41
	v_cvt_pk_bf16_f32 v23, v38, v39
	global_store_dwordx4 v[28:29], v[20:23], off offset:64
